# GEMM phases with a context split-K pass run the split-K pieces before the main round (staggers the memory-bound residual epilogues)
# speedup vs baseline: 1.0021x; 1.0021x over previous
;     __device__ void init(int mode_, int Mrows, int N, int G, int c, int nchunk_, int kchunk_) { mode = mode_; nchunk = nchunk_; kchunk = kchunk_; S.init(mode_ == 1 ? 64 * BM : Mrows, N, G, c); }
; #define LAS __attribute__((address_space(3)))
; template <class Epi> __device__ __forceinline__ void run_gemm(LAS unsigned char* lds, const bf16_t* A, const bf16_t* Bt, int N, int K, int lda, int blocked, int no_ctx, Epi E) {
;     const int npass = (N == 1024 && !no_ctx) ? 2 : 1;
;     for (int pass = 0; pass < npass; ++pass) {
;         pg8::Gemm g{A, Bt, M, N, pass ? 256 : K, lda, blocked}; pg8::SplitOrder S; S.init((N == 1024 || no_ctx) ? 1 + pass : 0, M, N, (int)gridDim.x, (int)blockIdx.x, K / 256, 256);
;         pg8::gemm_phase<Epi, pg8::SplitOrder, true, true>(lds, g, S, E);
;     }
; }
; __global__ void __launch_bounds__(512, 2) mega(Params Pk, int ph_lo, int ph_hi) {
;     ...
;             } else if (s == 1 || s == 2 || s == 4 || s == 7 || s == 9 || s == 10) {
;                 const int mode = (s == 1 || s == 9) ? 0 : (s == 4 ? 2 : 1);
;                 pg8::EpiAll E{ws, P->g_qn + l * 64, P->g_kn + l * 64, mode, l, s == 2 ? 2 : s == 7 ? 5 : 8, s == 7 ? 1.0f : 0.5f};
;                 const bf16_t* A = (s == 2 || s == 10) ? MID : XN;
;                 const bf16_t* Bt = WT + (mode == 0 ? WT_GU + (size_t)(s == 9 ? 1 : 0) * 5632 * 1024 : mode == 2 ? WT_IN : s == 7 ? WT_OUT : WT_DN + (size_t)(s == 10 ? 1 : 0) * 1024 * MIDP);
;                 const int N = mode == 0 ? 5632 : mode == 2 ? NIN : 1024, K = (s == 2 || s == 10) ? DFF : 1024;
;                 run_gemm(lds, A, Bt, N, K, (s == 2 || s == 10) ? DFF : 1024, (s == 2 || s == 10) ? 1 : 0, (l == 1 && s >= 7) ? 1 : 0, E);
.LBB0_126:
	v_readlane_b32 s14, v254, 28
	s_lshl_b32 s6, s14, 6
	s_ashr_i32 s7, s6, 31
	s_and_b64 s[2:3], s[12:13], exec
	s_movk_i32 s0, 0x1400
	v_readlane_b32 s19, v254, 29
	s_cselect_b32 s0, s0, 0x2000
	s_cmp_lg_u32 s19, 2
	s_cselect_b64 s[2:3], -1, 0
	v_cndmask_b32_e64 v170, 0.5, 1.0, s[12:13]
	s_and_b64 s[12:13], s[2:3], exec
	v_readlane_b32 s12, v254, 18
	v_readlane_b32 s13, v254, 19
	s_load_dwordx2 s[30:31], s[12:13], 0xb8
	s_cselect_b32 s0, s0, 0x800
	s_and_b64 s[2:3], s[2:3], s[10:11]
	s_and_b64 s[10:11], s[2:3], exec
	s_mov_b32 s10, 0x4200000
	s_cselect_b32 s10, s10, 0x6300000
	s_waitcnt lgkmcnt(0)
	s_add_u32 s68, s30, s10
	s_addc_u32 s59, s31, 0
	s_mul_i32 s11, s14, 0x26c0000
	s_mul_hi_i32 s10, s14, 0x26c0000
	s_add_u32 s12, s30, s11
	s_addc_u32 s13, s31, s10
	s_lshl_b64 s[10:11], s[26:27], 1
	s_add_u32 s10, s12, s10
	s_addc_u32 s11, s13, s11
	s_add_u32 s69, s10, 0xc050000
	s_addc_u32 s66, s11, 0
	s_cmp_eq_u32 s58, 2
	s_movk_i32 s10, 0x700
	s_cselect_b32 s10, s10, 0x400
	s_and_b64 s[8:9], s[8:9], exec
	s_cselect_b32 s14, 0x1600, s10
	s_and_b64 s[8:9], s[2:3], exec
	s_movk_i32 s8, 0xb00
	s_cselect_b32 s15, 0x400, s8
	s_add_i32 s8, s18, -13
	s_cmp_lt_u32 s8, 12
	s_cselect_b64 s[8:9], -1, 0
	s_cmp_gt_i32 s19, 6
	s_load_dword s67, s[20:21], 0x0
	s_cselect_b64 s[10:11], -1, 0
	s_and_b64 s[8:9], s[8:9], s[10:11]
	s_cmpk_eq_i32 s14, 0x400
	s_cselect_b64 s[10:11], -1, 0
	s_xor_b64 s[12:13], s[8:9], -1
	s_and_b64 s[18:19], s[10:11], s[12:13]
	s_or_b64 s[48:49], s[8:9], s[10:11]
	s_waitcnt lgkmcnt(0)
	s_ashr_i32 s28, s67, 31
	s_lshr_b32 s56, s15, 8
	s_lshr_b32 s23, s14, 8
	s_lshr_b32 s8, s15, 6
	v_writelane_b32 v254, s8, 36
	s_and_b64 s[8:9], s[2:3], exec
	s_mov_b32 s8, 0x40000
	s_cselect_b32 s20, 0x80, s22
	s_cselect_b32 s21, s8, 0x4000
	s_cselect_b32 s22, s39, 0x160000
	s_lshr_b32 s70, s14, 5
	s_lshr_b32 s10, s15, 5
	s_cmp_lt_i32 s98, s10
	s_cselect_b64 s[8:9], -1, 0
	v_writelane_b32 v254, s8, 37
	v_cvt_f32_ubyte1_e32 v1, s15
	v_rcp_iflag_f32_e32 v1, v1
	v_writelane_b32 v254, s9, 38
	s_and_b64 s[8:9], s[2:3], exec
	s_cselect_b32 s60, 7, 15
	s_lshl_b32 s0, s0, 2
	v_readlane_b32 s8, v254, 26
	s_add_u32 s71, s8, s0
	v_readlane_b32 s0, v254, 27
	s_addc_u32 s65, s0, 0
	s_add_u32 s0, s30, 0x10e00000
	v_writelane_b32 v254, s0, 39
	s_addc_u32 s0, s31, 0
	s_add_u32 s36, s30, 0x6300000
	s_addc_u32 s63, s31, 0
	s_add_u32 s8, s30, 0xc020000
	v_writelane_b32 v254, s0, 40
	s_addc_u32 s9, s31, 0
	v_writelane_b32 v254, s8, 41
	s_add_u32 s0, s30, 0x7000000
	s_mov_b32 s11, s27
	v_writelane_b32 v254, s9, 42
	v_writelane_b32 v254, s0, 43
	s_addc_u32 s0, s31, 0
	v_writelane_b32 v254, s0, 44
	s_add_u32 s0, s30, 0x7d00000
	v_writelane_b32 v254, s0, 45
	s_addc_u32 s0, s31, 0
	v_writelane_b32 v254, s0, 46
	s_add_u32 s0, s30, 0x8200000
	v_writelane_b32 v254, s0, 47
	s_addc_u32 s0, s31, 0
	v_writelane_b32 v254, s0, 48
	s_add_u32 s0, s30, 0x8700000
	v_writelane_b32 v254, s0, 49
	s_addc_u32 s0, s31, 0
	v_writelane_b32 v254, s0, 50
	s_add_u32 s0, s30, 0x8c00000
	v_writelane_b32 v254, s0, 51
	s_addc_u32 s0, s31, 0
	s_add_u32 s84, s30, 0xb100000
	s_addc_u32 s85, s31, 0
	s_add_u32 s72, s30, 0x9100000
	s_addc_u32 s73, s31, 0
	s_and_b64 s[2:3], s[2:3], exec
	v_writelane_b32 v254, s0, 52
	s_cselect_b32 s0, 10, 6
	s_abs_i32 s3, s70
	v_cvt_f32_u32_e32 v0, s3
	v_writelane_b32 v254, s0, 53
	v_writelane_b32 v254, s10, 54
	s_ashr_i32 s2, s70, 31
	v_rcp_iflag_f32_e32 v0, v0
	v_writelane_b32 v254, s11, 55
	v_writelane_b32 v254, s2, 56
	s_sub_i32 s2, 0, s3
	v_mul_f32_e32 v0, 0x4f7ffffe, v0
	v_cvt_u32_f32_e32 v0, v0
	s_mov_b32 s0, 1
	v_writelane_b32 v255, s18, 0
	s_mov_b64 s[30:31], -1
	v_readfirstlane_b32 s8, v0
	v_mul_f32_e32 v0, 0x4f7ffffe, v1
	v_cvt_u32_f32_e32 v0, v0
	s_mul_i32 s2, s2, s8
	s_mul_hi_u32 s2, s8, s2
	s_add_i32 s2, s8, s2
	v_writelane_b32 v254, s2, 57
	s_sub_i32 s2, 0, s56
	v_readfirstlane_b32 s8, v0
	s_mul_i32 s2, s2, s8
	s_mul_hi_u32 s2, s8, s2
	s_add_i32 s2, s8, s2
	v_readlane_b32 s9, v254, 2
	v_writelane_b32 v254, s2, 58
	s_mul_hi_u32 s2, s9, s2
	s_mul_i32 s8, s2, s56
	s_sub_i32 s8, s9, s8
	s_add_i32 s9, s2, 1
	s_sub_i32 s10, s8, s56
	s_cmp_ge_u32 s8, s56
	s_cselect_b32 s2, s9, s2
	s_cselect_b32 s8, s10, s8
	s_add_i32 s9, s2, 1
	s_cmp_ge_u32 s8, s56
	s_cselect_b32 s2, s9, s2
	s_xor_b32 s2, s2, s99
	s_sub_i32 s2, s2, s99
	s_mul_i32 s8, s2, s56
	s_sub_i32 s8, s98, s8
	s_cmp_lt_u32 s2, 4
	s_cselect_b32 s9, 32, 0x41
	v_writelane_b32 v254, s9, 59
	s_and_b32 s2, s2, 3
	v_writelane_b32 v254, s2, 60
	s_lshl_b32 s2, s8, 8
	v_writelane_b32 v255, s19, 1
	v_writelane_b32 v254, s2, 61
	s_lshl_b64 s[6:7], s[6:7], 2
	v_writelane_b32 v255, s48, 2
	v_writelane_b32 v254, s6, 62
	v_mov_b32_e32 v172, v170
	v_writelane_b32 v255, s49, 3
	v_mov_b32_e32 v173, v170
	v_writelane_b32 v254, s7, 63
	v_writelane_b32 v255, s23, 4
	s_mov_b32 s100, 0
	s_and_b64 vcc, exec, s[18:19]
	s_cbranch_vccz .Lpp_single
	s_mov_b32 s0, 2
	s_mov_b64 s[30:31], 0
	s_mov_b32 s100, 1
.Lpp_single:
	s_branch .LBB0_129
.LBB0_127:
	s_waitcnt vmcnt(0)
	v_readlane_b32 s18, v255, 0
	v_readlane_b32 s48, v255, 2
	v_readlane_b32 s30, v255, 9
	s_mov_b32 s88, 0x3c000
	s_mov_b32 s89, 0x39000
	s_mov_b32 s86, 0x37000
	s_mov_b32 s87, 0x33000
	v_readlane_b32 s19, v255, 1
	v_readlane_b32 s49, v255, 3
	v_readlane_b32 s23, v255, 4
	v_readlane_b32 s31, v255, 10
	s_barrier
.LBB0_128:
	s_cmp_eq_u32 s100, 0
	s_cbranch_scc1 .LBB0_345
	s_mov_b32 s100, 0
	s_mov_b32 s0, 1
	s_mov_b64 s[30:31], -1

; __global__ void __launch_bounds__(512, 2) mega(Params Pk, int ph_lo, int ph_hi) {
	.amdhsa_kernel _Z4mega6Paramsii
		.amdhsa_group_segment_fixed_size 0
		.amdhsa_private_segment_fixed_size 0
		.amdhsa_kernarg_size 456
		.amdhsa_user_sgpr_count 2
		.amdhsa_user_sgpr_dispatch_ptr 0
		.amdhsa_user_sgpr_queue_ptr 0
		.amdhsa_user_sgpr_kernarg_segment_ptr 1
		.amdhsa_user_sgpr_dispatch_id 0
		.amdhsa_user_sgpr_kernarg_preload_length 0
		.amdhsa_user_sgpr_kernarg_preload_offset 0
		.amdhsa_user_sgpr_private_segment_size 0
		.amdhsa_uses_dynamic_stack 0
		.amdhsa_enable_private_segment 0
		.amdhsa_system_sgpr_workgroup_id_x 1
		.amdhsa_system_sgpr_workgroup_id_y 0
		.amdhsa_system_sgpr_workgroup_id_z 0
		.amdhsa_system_sgpr_workgroup_info 0
		.amdhsa_system_vgpr_workitem_id 2
		.amdhsa_next_free_vgpr 256
		.amdhsa_next_free_sgpr 102
		.amdhsa_accum_offset 256
		.amdhsa_reserve_vcc 1
		.amdhsa_float_round_mode_32 0
		.amdhsa_float_round_mode_16_64 0
		.amdhsa_float_denorm_mode_32 3
		.amdhsa_float_denorm_mode_16_64 3
		.amdhsa_dx10_clamp 1
		.amdhsa_ieee_mode 1
		.amdhsa_fp16_overflow 0
		.amdhsa_tg_split 0
		.amdhsa_exception_fp_ieee_invalid_op 0
		.amdhsa_exception_fp_denorm_src 0
		.amdhsa_exception_fp_ieee_div_zero 0
		.amdhsa_exception_fp_ieee_overflow 0
		.amdhsa_exception_fp_ieee_underflow 0
		.amdhsa_exception_fp_ieee_inexact 0
		.amdhsa_exception_int_div_zero 0
	.end_amdhsa_kernel

; __global__ void __launch_bounds__(512, 2) mega(Params Pk, int ph_lo, int ph_hi) {
amdhsa.kernels:
  - .agpr_count:     0
    .args:
      - .offset:         0
        .size:           192
        .value_kind:     by_value
      - .offset:         192
        .size:           4
        .value_kind:     by_value
      - .offset:         196
        .size:           4
        .value_kind:     by_value
      - .offset:         200
        .size:           4
        .value_kind:     hidden_block_count_x
      - .offset:         204
        .size:           4
        .value_kind:     hidden_block_count_y
      - .offset:         208
        .size:           4
        .value_kind:     hidden_block_count_z
      - .offset:         212
        .size:           2
        .value_kind:     hidden_group_size_x
      - .offset:         214
        .size:           2
        .value_kind:     hidden_group_size_y
      - .offset:         216
        .size:           2
        .value_kind:     hidden_group_size_z
      - .offset:         218
        .size:           2
        .value_kind:     hidden_remainder_x
      - .offset:         220
        .size:           2
        .value_kind:     hidden_remainder_y
      - .offset:         222
        .size:           2
        .value_kind:     hidden_remainder_z
      - .offset:         240
        .size:           8
        .value_kind:     hidden_global_offset_x
      - .offset:         248
        .size:           8
        .value_kind:     hidden_global_offset_y
      - .offset:         256
        .size:           8
        .value_kind:     hidden_global_offset_z
      - .offset:         264
        .size:           2
        .value_kind:     hidden_grid_dims
      - .offset:         288
        .size:           8
        .value_kind:     hidden_multigrid_sync_arg
      - .offset:         320
        .size:           4
        .value_kind:     hidden_dynamic_lds_size
    .group_segment_fixed_size: 0
    .kernarg_segment_align: 8
    .kernarg_segment_size: 456
    .language:       OpenCL C
    .language_version:
      - 2
      - 0
    .max_flat_workgroup_size: 512
    .name:           _Z4mega6Paramsii
    .private_segment_fixed_size: 0
    .sgpr_count:     108
    .sgpr_spill_count: 83
    .symbol:         _Z4mega6Paramsii.kd
    .uniform_work_group_size: 1
    .uses_dynamic_stack: false
    .vgpr_count:     256
    .vgpr_spill_count: 0
    .wavefront_size: 64
